# v94 + mLSTM scan wait/nop slimming: staging vmcnt ladder collapsed to one wait, compiler pad nops between prefetch loads dropped
# baseline (speedup 1.0000x reference)
.LBB0_208:
	s_waitcnt lgkmcnt(0)
	s_barrier
	s_waitcnt vmcnt(0)
	ds_write_b128 v189, v[0:3]
	ds_write_b128 v189, v[4:7] offset:34816
	v_alignbit_b32 v72, v9, v9, 16
	v_alignbit_b32 v73, v8, v8, 16
	v_cndmask_b32_e64 v80, v73, v11, s[2:3]
	v_cndmask_b32_e64 v81, v72, v10, s[2:3]
	ds_read_b128 v[72:75], v156
	v_alignbit_b32 v76, v11, v11, 16
	v_cndmask_b32_e64 v83, v76, v8, s[2:3]
	v_alignbit_b32 v77, v10, v10, 16
	v_lshlrev_b32_e32 v84, 16, v83
	v_and_b32_e32 v83, 0xffff0000, v83
	v_cndmask_b32_e64 v82, v77, v9, s[2:3]
	ds_read_b128 v[76:79], v156 offset:16
	ds_read_b128 v[246:249], v156
	ds_read_b128 v[250:253], v156 offset:16
	s_waitcnt lgkmcnt(1)
	v_mul_f32_e32 v72, v72, v84
	v_mul_f32_e32 v73, v73, v83
	v_cvt_pk_bf16_f32 v72, v72, v73
	v_lshlrev_b32_e32 v73, 16, v82
	v_mul_f32_e32 v73, v74, v73
	v_and_b32_e32 v74, 0xffff0000, v82
	v_mul_f32_e32 v74, v75, v74
	v_cvt_pk_bf16_f32 v73, v73, v74
	v_lshlrev_b32_e32 v74, 16, v81
	v_and_b32_e32 v75, 0xffff0000, v81
	s_waitcnt lgkmcnt(0)
	v_mul_f32_e32 v74, v76, v74
	v_mul_f32_e32 v75, v77, v75
	v_cvt_pk_bf16_f32 v74, v74, v75
	v_lshlrev_b32_e32 v75, 16, v80
	v_mul_f32_e32 v75, v78, v75
	v_and_b32_e32 v76, 0xffff0000, v80
	v_mul_f32_e32 v76, v79, v76
	v_cvt_pk_bf16_f32 v75, v75, v76
	ds_write_b128 v190, v[72:75]
	ds_write_b128 v192, v[12:15]
	ds_write_b128 v192, v[16:19] offset:34816
	v_alignbit_b32 v72, v21, v21, 16
	v_alignbit_b32 v73, v20, v20, 16
	v_cndmask_b32_e64 v80, v73, v23, s[2:3]
	v_cndmask_b32_e64 v81, v72, v22, s[2:3]
	v_alignbit_b32 v76, v23, v23, 16
	v_cndmask_b32_e64 v83, v76, v20, s[2:3]
	v_alignbit_b32 v77, v22, v22, 16
	v_lshlrev_b32_e32 v84, 16, v83
	v_and_b32_e32 v83, 0xffff0000, v83
	v_cndmask_b32_e64 v82, v77, v21, s[2:3]
	v_mul_f32_e32 v72, v246, v84
	v_mul_f32_e32 v73, v247, v83
	v_cvt_pk_bf16_f32 v72, v72, v73
	v_lshlrev_b32_e32 v73, 16, v82
	v_mul_f32_e32 v73, v248, v73
	v_and_b32_e32 v74, 0xffff0000, v82
	v_mul_f32_e32 v74, v249, v74
	v_cvt_pk_bf16_f32 v73, v73, v74
	v_lshlrev_b32_e32 v74, 16, v81
	v_and_b32_e32 v75, 0xffff0000, v81
	v_mul_f32_e32 v74, v250, v74
	v_mul_f32_e32 v75, v251, v75
	v_cvt_pk_bf16_f32 v74, v74, v75
	v_lshlrev_b32_e32 v75, 16, v80
	v_mul_f32_e32 v75, v252, v75
	v_and_b32_e32 v76, 0xffff0000, v80
	v_mul_f32_e32 v76, v253, v76
	v_cvt_pk_bf16_f32 v75, v75, v76
	ds_write_b128 v193, v[72:75]
	ds_write_b128 v194, v[24:27]
	ds_write_b128 v194, v[28:31] offset:34816
	v_alignbit_b32 v72, v33, v33, 16
	v_alignbit_b32 v73, v32, v32, 16
	v_cndmask_b32_e64 v80, v73, v35, s[2:3]
	v_cndmask_b32_e64 v81, v72, v34, s[2:3]
	v_alignbit_b32 v76, v35, v35, 16
	v_cndmask_b32_e64 v83, v76, v32, s[2:3]
	v_alignbit_b32 v77, v34, v34, 16
	v_lshlrev_b32_e32 v84, 16, v83
	v_and_b32_e32 v83, 0xffff0000, v83
	v_cndmask_b32_e64 v82, v77, v33, s[2:3]
	v_mul_f32_e32 v72, v246, v84
	v_mul_f32_e32 v73, v247, v83
	v_cvt_pk_bf16_f32 v72, v72, v73
	v_lshlrev_b32_e32 v73, 16, v82
	v_mul_f32_e32 v73, v248, v73
	v_and_b32_e32 v74, 0xffff0000, v82
	v_mul_f32_e32 v74, v249, v74
	v_cvt_pk_bf16_f32 v73, v73, v74
	v_lshlrev_b32_e32 v74, 16, v81
	v_and_b32_e32 v75, 0xffff0000, v81
	v_mul_f32_e32 v74, v250, v74
	v_mul_f32_e32 v75, v251, v75
	v_cvt_pk_bf16_f32 v74, v74, v75
	v_lshlrev_b32_e32 v75, 16, v80
	v_mul_f32_e32 v75, v252, v75
	v_and_b32_e32 v76, 0xffff0000, v80
	v_mul_f32_e32 v76, v253, v76
	v_cvt_pk_bf16_f32 v75, v75, v76
	ds_write_b128 v195, v[72:75]
	ds_write_b128 v196, v[36:39]
	ds_write_b128 v196, v[40:43] offset:34816
	v_alignbit_b32 v72, v45, v45, 16
	v_alignbit_b32 v73, v44, v44, 16
	v_cndmask_b32_e64 v80, v73, v47, s[2:3]
	v_cndmask_b32_e64 v81, v72, v46, s[2:3]
	v_alignbit_b32 v76, v47, v47, 16
	v_cndmask_b32_e64 v83, v76, v44, s[2:3]
	v_alignbit_b32 v77, v46, v46, 16
	v_lshlrev_b32_e32 v84, 16, v83
	v_and_b32_e32 v83, 0xffff0000, v83
	v_cndmask_b32_e64 v82, v77, v45, s[2:3]
	v_mul_f32_e32 v72, v246, v84
	v_mul_f32_e32 v73, v247, v83
	v_cvt_pk_bf16_f32 v72, v72, v73
	v_lshlrev_b32_e32 v73, 16, v82
	v_mul_f32_e32 v73, v248, v73
	v_and_b32_e32 v74, 0xffff0000, v82
	v_mul_f32_e32 v74, v249, v74
	v_cvt_pk_bf16_f32 v73, v73, v74
	v_lshlrev_b32_e32 v74, 16, v81
	v_and_b32_e32 v75, 0xffff0000, v81
	v_mul_f32_e32 v74, v250, v74
	v_mul_f32_e32 v75, v251, v75
	v_cvt_pk_bf16_f32 v74, v74, v75
	v_lshlrev_b32_e32 v75, 16, v80
	v_mul_f32_e32 v75, v252, v75
	v_and_b32_e32 v76, 0xffff0000, v80
	v_mul_f32_e32 v76, v253, v76
	v_cvt_pk_bf16_f32 v75, v75, v76
	ds_write_b128 v197, v[72:75]
	v_alignbit_b32 v72, v51, v51, 16
	v_alignbit_b32 v73, v50, v50, 16
	v_alignbit_b32 v74, v49, v49, 16
	v_alignbit_b32 v75, v48, v48, 16
	v_cndmask_b32_e64 v75, v75, v51, s[2:3]
	v_cndmask_b32_e64 v74, v74, v50, s[2:3]
	v_cndmask_b32_e64 v73, v73, v49, s[2:3]
	v_cndmask_b32_e64 v72, v72, v48, s[2:3]
	v_add_u32_e32 v76, v168, v188
	ds_write_b128 v76, v[72:75]
	v_alignbit_b32 v72, v55, v55, 16
	v_alignbit_b32 v73, v54, v54, 16
	v_alignbit_b32 v74, v53, v53, 16
	v_alignbit_b32 v75, v52, v52, 16
	v_cndmask_b32_e64 v75, v75, v55, s[2:3]
	v_cndmask_b32_e64 v74, v74, v54, s[2:3]
	v_cndmask_b32_e64 v73, v73, v53, s[2:3]
	v_cndmask_b32_e64 v72, v72, v52, s[2:3]
	v_add_u32_e32 v76, v168, v191
	v_mov_b32_e32 v88, 0
	ds_write_b128 v76, v[72:75]
	s_mov_b32 s85, 0
	v_mov_b32_e32 v89, v88
	v_mov_b32_e32 v90, v88
	v_mov_b32_e32 v91, v88
	v_mov_b32_e32 v92, v88
	v_mov_b32_e32 v93, v88
	v_mov_b32_e32 v94, v88
	v_mov_b32_e32 v95, v88
	v_mov_b32_e32 v100, v88
	v_mov_b32_e32 v101, v88
	v_mov_b32_e32 v102, v88
	v_mov_b32_e32 v103, v88
	v_mov_b32_e32 v108, v88
	v_mov_b32_e32 v109, v88
	v_mov_b32_e32 v110, v88
	v_mov_b32_e32 v111, v88
	v_mov_b32_e32 v96, v88
	v_mov_b32_e32 v97, v88
	v_mov_b32_e32 v98, v88
	v_mov_b32_e32 v99, v88
	v_mov_b32_e32 v104, v88
	v_mov_b32_e32 v105, v88
	v_mov_b32_e32 v106, v88
	v_mov_b32_e32 v107, v88
	v_mov_b32_e32 v112, v88
	v_mov_b32_e32 v113, v88
	v_mov_b32_e32 v114, v88
	v_mov_b32_e32 v115, v88
	v_mov_b32_e32 v116, v88
	v_mov_b32_e32 v117, v88
	v_mov_b32_e32 v118, v88
	v_mov_b32_e32 v119, v88
	v_mov_b32_e32 v72, v88
	v_mov_b32_e32 v73, v88
	v_mov_b32_e32 v74, v88
	v_mov_b32_e32 v75, v88
	v_mov_b32_e32 v76, v88
	v_mov_b32_e32 v77, v88
	v_mov_b32_e32 v78, v88
	v_mov_b32_e32 v79, v88
	v_mov_b32_e32 v80, v88
	v_mov_b32_e32 v81, v88
	v_mov_b32_e32 v82, v88
	v_mov_b32_e32 v83, v88
	v_mov_b32_e32 v84, v88
	v_mov_b32_e32 v85, v88
	v_mov_b32_e32 v86, v88
	v_mov_b32_e32 v87, v88
	s_waitcnt lgkmcnt(0)
	s_barrier
	s_add_i32 s99, s84, 1
	s_cmp_ge_u32 s99, s95
	s_cbranch_scc1 .Lpf_skip
	s_lshl_b32 s100, s99, 7
	s_sub_i32 s101, s94, s100
	s_and_b64 s[86:87], s[2:3], exec
	s_cselect_b32 s100, s100, s101
	s_add_i32 s100, s100, s89
	s_ashr_i32 s101, s100, 7
	v_add_u32_e32 v0, s100, v148
	v_add_u32_e32 v12, s100, v150
	v_add_u32_e32 v24, s100, v151
	v_add_u32_e32 v36, s100, v152
	v_ashrrev_i32_e32 v1, 31, v0
	v_mad_i64_i32 v[8:9], s[86:87], s101, v149, v[136:137]
	v_ashrrev_i32_e32 v13, 31, v12
	v_mad_i64_i32 v[20:21], s[86:87], s101, v149, v[138:139]
	v_ashrrev_i32_e32 v25, 31, v24
	v_mad_i64_i32 v[32:33], s[86:87], s101, v149, v[140:141]
	v_ashrrev_i32_e32 v37, 31, v36
	v_mad_i64_i32 v[46:47], s[86:87], s101, v149, v[142:143]
	v_lshlrev_b64 v[0:1], 8, v[0:1]
	v_lshlrev_b64 v[44:45], 8, v[8:9]
	v_lshlrev_b64 v[12:13], 8, v[12:13]
	v_lshlrev_b64 v[52:53], 8, v[20:21]
	v_lshlrev_b64 v[24:25], 8, v[24:25]
	v_lshlrev_b64 v[32:33], 8, v[32:33]
	v_lshlrev_b64 v[36:37], 8, v[36:37]
	v_lshlrev_b64 v[46:47], 8, v[46:47]
	v_lshl_add_u64 v[2:3], v[128:129], 0, v[0:1]
	v_lshl_add_u64 v[4:5], v[130:131], 0, v[0:1]
	v_lshl_add_u64 v[8:9], v[132:133], 0, v[44:45]
	v_lshl_add_u64 v[14:15], v[128:129], 0, v[12:13]
	v_lshl_add_u64 v[16:17], v[130:131], 0, v[12:13]
	v_lshl_add_u64 v[20:21], v[132:133], 0, v[52:53]
	v_lshl_add_u64 v[26:27], v[128:129], 0, v[24:25]
	v_lshl_add_u64 v[28:29], v[130:131], 0, v[24:25]
	v_lshl_add_u64 v[32:33], v[132:133], 0, v[32:33]
	v_lshl_add_u64 v[38:39], v[128:129], 0, v[36:37]
	v_lshl_add_u64 v[40:41], v[130:131], 0, v[36:37]
	v_lshl_add_u64 v[46:47], v[132:133], 0, v[46:47]
	v_lshl_add_u64 v[48:49], v[144:145], 0, v[44:45]
	v_lshl_add_u64 v[52:53], v[144:145], 0, v[52:53]
	global_load_dwordx4 v[0:3], v[2:3], off
	global_load_dwordx4 v[4:7], v[4:5], off
	global_load_dwordx4 v[8:11], v[8:9], off
	global_load_dwordx4 v[12:15], v[14:15], off
	global_load_dwordx4 v[16:19], v[16:17], off
	global_load_dwordx4 v[20:23], v[20:21], off
	global_load_dwordx4 v[24:27], v[26:27], off
	global_load_dwordx4 v[28:31], v[28:29], off
	global_load_dwordx4 v[32:35], v[32:33], off
	global_load_dwordx4 v[36:39], v[38:39], off
	global_load_dwordx4 v[40:43], v[40:41], off
	global_load_dwordx4 v[44:47], v[46:47], off
	global_load_dwordx4 v[48:51], v[48:49], off
	global_load_dwordx4 v[52:55], v[52:53], off
	s_and_saveexec_b64 s[86:87], s[0:1]
	s_cbranch_execz .Lpf_215
	v_add_u32_e32 v120, s100, v153
	s_waitcnt lgkmcnt(0)
	v_ashrrev_i32_e32 v121, 31, v120
	v_readlane_b32 s100, v255, 10
	v_lshlrev_b64 v[120:121], 6, v[120:121]
	v_readlane_b32 s101, v255, 11
	s_nop 1
	v_lshl_add_u64 v[120:121], s[100:101], 0, v[120:121]
	global_load_dword v154, v[120:121], off
	global_load_dword v155, v[120:121], off offset:16
